# MFMA order: k0,k1 back-to-back per accumulator in all three GEMM loops
# speedup vs baseline: 1.0050x; 1.0050x over previous
; #define PG8_STAGE(bufoff, gbase, voff) do { _Pragma("unroll") for (int _i = 0; _i < 2; ++_i) \
;         __builtin_amdgcn_global_load_lds((const unsigned*)((const char*)(gbase) + (voff)[_i]), (PG8_LAS unsigned*)(lds + (bufoff) + ldsw + _i * 8192), 16, 0, 0); } while (0)
; #define PG8_LDA(dst, b, h) do { _Pragma("unroll") for (int m = 0; m < 4; ++m) _Pragma("unroll") for (int k = 0; k < 2; ++k) dst[m][k] = *(const PG8_LAS bf16x8*)(lds + PG8_SA(b, h) + aoff + m * 2048 + k * 1024); } while (0)
; #define PG8_LDB(dst, b, h) do { _Pragma("unroll") for (int n = 0; n < 2; ++n) _Pragma("unroll") for (int k = 0; k < 2; ++k) dst[n][k] = *(const PG8_LAS bf16x8*)(lds + PG8_SB(b, h) + boff + n * 2048 + k * 1024); } while (0)
; #define PG8_MMA(ai, bj, At, Bt) do { __builtin_amdgcn_s_setprio(1); _Pragma("unroll") for (int m = 0; m < 4; ++m) _Pragma("unroll") for (int n = 0; n < 2; ++n) _Pragma("unroll") for (int k = 0; k < 2; ++k) \
;         acc[ai][bj][m][n] = __builtin_amdgcn_mfma_f32_16x16x32_bf16(Bt[n][k], At[m][k], acc[ai][bj][m][n], 0, 0, 0); __builtin_amdgcn_s_setprio(0); } while (0)
; #define PG8_WAIT_V(n) asm volatile("s_waitcnt vmcnt(" #n ")" ::: "memory")
; #define PG8_WAIT_L(n) asm volatile("s_waitcnt lgkmcnt(" #n ")" ::: "memory")
; template <class Epi, class Sched, bool ALIGN_EPI = false, bool SP2 = false>
; __device__ __forceinline__ void gemm_phase(PG8_LAS unsigned char* lds, const Gemm g, const Sched& S, const Epi& E) {
;     ...
;             const bool last = (t == nt - 2);
;             const char* a1 = cA + (size_t)(t + 1) * kstepA;
;             const char* a2 = last ? nA : cA + (size_t)(t + 2) * kstepA; const char* b2 = last ? nB : cB + (size_t)(t + 2) * kstep;
;             const char* a3 = a2 + kstepA; const char* b3 = b2 + kstep;
;             if (last && has_next) S.a_ready(nxt);
;             if constexpr (SP2) {
;             PG8_LDB(B0, 0, 0); PG8_LDB(B1, 0, 1); PG8_SCHED; PG8_LDA(At, 0, 0); PG8_STAGE(PG8_SA(1, 1), a1 + hstep, voffA);
;             PG8_WAIT_V(8); PG8_WAIT_L(0); PG8_BAR; PG8_MMA(0, 0, At, B0); PG8_MMA(0, 1, At, B1); PG8_BAR; PG8_SCHED;
;             PG8_LDA(At, 0, 1); PG8_STAGE(PG8_SB(0, 0), b2, voffB); PG8_STAGE(PG8_SB(0, 1), b2 + hstep, voffB); PG8_STAGE(PG8_SA(0, 0), a2, voffA);
;             PG8_WAIT_V(8); PG8_WAIT_L(0); PG8_BAR; PG8_MMA(1, 0, At, B0); PG8_MMA(1, 1, At, B1); PG8_BAR; PG8_SCHED;
.LBB0_238:
	s_add_u32 s2, s24, 0x8000
	s_addc_u32 s3, s25, 0
	s_cmp_eq_u32 s71, 12
	s_cselect_b32 s46, s67, s2
	s_cselect_b32 s47, s11, s3
	s_cselect_b32 s42, s68, s69
	s_cselect_b32 s43, s9, s70
	s_add_u32 s26, s46, 0x4000
	s_addc_u32 s27, s47, 0
	v_add_u32_e32 v148, s76, v150
	s_add_i32 s72, 0, 0x14000
	ds_read_b128 v[144:147], v148
	ds_read_b128 v[160:163], v148 offset:1024
	ds_read_b128 v[164:167], v148 offset:2048
	ds_read_b128 v[168:171], v148 offset:3072
	v_add_u32_e32 v148, s72, v150
	ds_read_b128 v[172:175], v148
	ds_read_b128 v[176:179], v148 offset:1024
	ds_read_b128 v[180:183], v148 offset:2048
	ds_read_b128 v[184:187], v148 offset:3072
	v_lshl_add_u64 v[148:149], s[24:25], 0, v[142:143]
	s_add_i32 m0, s23, 0xc000
	ds_read_b128 v[188:191], v152
	ds_read_b128 v[206:209], v152 offset:1024
	ds_read_b128 v[210:213], v152 offset:2048
	ds_read_b128 v[214:217], v152 offset:3072
	ds_read_b128 v[218:221], v152 offset:4096
	ds_read_b128 v[222:225], v152 offset:5120
	ds_read_b128 v[226:229], v152 offset:6144
	ds_read_b128 v[230:233], v152 offset:7168
	global_load_lds_dwordx4 v[148:149], off
	v_lshl_add_u64 v[148:149], s[24:25], 0, v[140:141]
	s_add_i32 m0, s23, 0xe000
	s_nop 0
	global_load_lds_dwordx4 v[148:149], off
	s_waitcnt vmcnt(8)
	s_waitcnt lgkmcnt(0)
	s_barrier
	s_setprio 1
	s_waitcnt lgkmcnt(0)
	v_mfma_f32_16x16x32_bf16 v[126:129], v[144:147], v[188:191], v[126:129]
	v_mfma_f32_16x16x32_bf16 v[126:129], v[160:163], v[206:209], v[126:129]
	v_mfma_f32_16x16x32_bf16 v[122:125], v[164:167], v[188:191], v[122:125]
	v_mfma_f32_16x16x32_bf16 v[122:125], v[168:171], v[206:209], v[122:125]
	v_mfma_f32_16x16x32_bf16 v[110:113], v[144:147], v[210:213], v[110:113]
	v_mfma_f32_16x16x32_bf16 v[110:113], v[160:163], v[214:217], v[110:113]
	v_mfma_f32_16x16x32_bf16 v[106:109], v[164:167], v[210:213], v[106:109]
	v_mfma_f32_16x16x32_bf16 v[106:109], v[168:171], v[214:217], v[106:109]
	v_mfma_f32_16x16x32_bf16 v[94:97], v[144:147], v[218:221], v[94:97]
	v_mfma_f32_16x16x32_bf16 v[94:97], v[160:163], v[222:225], v[94:97]
	v_mfma_f32_16x16x32_bf16 v[90:93], v[164:167], v[218:221], v[90:93]
	v_mfma_f32_16x16x32_bf16 v[90:93], v[168:171], v[222:225], v[90:93]
	v_mfma_f32_16x16x32_bf16 v[78:81], v[144:147], v[226:229], v[78:81]
	v_mfma_f32_16x16x32_bf16 v[78:81], v[160:163], v[230:233], v[78:81]
	v_mfma_f32_16x16x32_bf16 v[74:77], v[164:167], v[226:229], v[74:77]
	v_mfma_f32_16x16x32_bf16 v[74:77], v[168:171], v[230:233], v[74:77]
	s_setprio 0
	s_setprio 1
	v_mfma_f32_16x16x32_bf16 v[118:121], v[172:175], v[188:191], v[118:121]
	v_mfma_f32_16x16x32_bf16 v[118:121], v[176:179], v[206:209], v[118:121]
	v_mfma_f32_16x16x32_bf16 v[114:117], v[180:183], v[188:191], v[114:117]
	v_mfma_f32_16x16x32_bf16 v[114:117], v[184:187], v[206:209], v[114:117]
	v_mfma_f32_16x16x32_bf16 v[102:105], v[172:175], v[210:213], v[102:105]
	v_mfma_f32_16x16x32_bf16 v[102:105], v[176:179], v[214:217], v[102:105]
	v_mfma_f32_16x16x32_bf16 v[98:101], v[180:183], v[210:213], v[98:101]
	v_mfma_f32_16x16x32_bf16 v[98:101], v[184:187], v[214:217], v[98:101]
	v_mfma_f32_16x16x32_bf16 v[86:89], v[172:175], v[218:221], v[86:89]
	v_mfma_f32_16x16x32_bf16 v[86:89], v[176:179], v[222:225], v[86:89]
	v_mfma_f32_16x16x32_bf16 v[82:85], v[180:183], v[218:221], v[82:85]
	v_mfma_f32_16x16x32_bf16 v[82:85], v[184:187], v[222:225], v[82:85]
	v_mfma_f32_16x16x32_bf16 v[70:73], v[172:175], v[226:229], v[70:73]
	v_mfma_f32_16x16x32_bf16 v[70:73], v[176:179], v[230:233], v[70:73]
	v_mfma_f32_16x16x32_bf16 v[66:69], v[180:183], v[226:229], v[66:69]
	v_mfma_f32_16x16x32_bf16 v[66:69], v[184:187], v[230:233], v[66:69]
	s_setprio 0
	s_barrier
	s_add_i32 s24, s76, s51
	v_lshl_add_u64 v[148:149], s[42:43], 0, v[132:133]
	s_mov_b32 m0, s24
	ds_read_b128 v[188:191], v152 offset:16384
	ds_read_b128 v[206:209], v152 offset:17408
	ds_read_b128 v[210:213], v152 offset:18432
	ds_read_b128 v[214:217], v152 offset:19456
	ds_read_b128 v[218:221], v152 offset:20480
	ds_read_b128 v[222:225], v152 offset:21504
	ds_read_b128 v[226:229], v152 offset:22528
	ds_read_b128 v[230:233], v152 offset:23552
	global_load_lds_dwordx4 v[148:149], off
	s_add_i32 m0, s24, 0x2000
	s_add_u32 s24, s42, 0x40000
	v_lshl_add_u64 v[234:235], s[42:43], 0, v[136:137]
	s_addc_u32 s25, s43, 0
	s_add_i32 s72, s72, s51
	global_load_lds_dwordx4 v[234:235], off
	v_lshl_add_u64 v[236:237], s[24:25], 0, v[132:133]
	s_mov_b32 m0, s72
	s_nop 0
	global_load_lds_dwordx4 v[236:237], off
	v_lshl_add_u64 v[236:237], s[24:25], 0, v[136:137]
	s_add_i32 m0, s72, 0x2000
	s_nop 0
	global_load_lds_dwordx4 v[236:237], off
	v_lshl_add_u64 v[236:237], s[46:47], 0, v[130:131]
	s_mov_b32 m0, s23
	s_nop 0
	global_load_lds_dwordx4 v[236:237], off
	v_lshl_add_u64 v[236:237], s[46:47], 0, v[134:135]
	s_mov_b32 m0, s56
	s_nop 0
	global_load_lds_dwordx4 v[236:237], off
	s_waitcnt vmcnt(8)
	s_waitcnt lgkmcnt(0)
	s_barrier
; #define PG8_STAGE(bufoff, gbase, voff) do { _Pragma("unroll") for (int _i = 0; _i < 2; ++_i) \
;         __builtin_amdgcn_global_load_lds((const unsigned*)((const char*)(gbase) + (voff)[_i]), (PG8_LAS unsigned*)(lds + (bufoff) + ldsw + _i * 8192), 16, 0, 0); } while (0)
; #define PG8_LDA(dst, b, h) do { _Pragma("unroll") for (int m = 0; m < 4; ++m) _Pragma("unroll") for (int k = 0; k < 2; ++k) dst[m][k] = *(const PG8_LAS bf16x8*)(lds + PG8_SA(b, h) + aoff + m * 2048 + k * 1024); } while (0)
; #define PG8_LDB(dst, b, h) do { _Pragma("unroll") for (int n = 0; n < 2; ++n) _Pragma("unroll") for (int k = 0; k < 2; ++k) dst[n][k] = *(const PG8_LAS bf16x8*)(lds + PG8_SB(b, h) + boff + n * 2048 + k * 1024); } while (0)
; #define PG8_MMA(ai, bj, At, Bt) do { __builtin_amdgcn_s_setprio(1); _Pragma("unroll") for (int m = 0; m < 4; ++m) _Pragma("unroll") for (int n = 0; n < 2; ++n) _Pragma("unroll") for (int k = 0; k < 2; ++k) \
;         acc[ai][bj][m][n] = __builtin_amdgcn_mfma_f32_16x16x32_bf16(Bt[n][k], At[m][k], acc[ai][bj][m][n], 0, 0, 0); __builtin_amdgcn_s_setprio(0); } while (0)
; #define PG8_WAIT_V(n) asm volatile("s_waitcnt vmcnt(" #n ")" ::: "memory")
; #define PG8_WAIT_L(n) asm volatile("s_waitcnt lgkmcnt(" #n ")" ::: "memory")
; #define PG8_BAR __builtin_amdgcn_s_barrier()
; #define PG8_SCHED __builtin_amdgcn_sched_barrier(0)
; template <class Epi, class Sched, bool ALIGN_EPI = false, bool SP2 = false>
; __device__ __forceinline__ void gemm_phase(PG8_LAS unsigned char* lds, const Gemm g, const Sched& S, const Epi& E) {
;     ...
;             PG8_WAIT_V(8); PG8_WAIT_L(0); PG8_BAR; PG8_MMA(1, 0, At, B0); PG8_MMA(1, 1, At, B1); PG8_BAR; PG8_SCHED;
;             PG8_LDB(B0, 1, 0); PG8_LDB(B1, 1, 1); PG8_SCHED; PG8_LDA(At, 1, 0); PG8_STAGE(PG8_SA(0, 1), a2 + hstep, voffA);
;             PG8_WAIT_V(8); PG8_WAIT_L(0); PG8_BAR; PG8_MMA(0, 0, At, B0); PG8_MMA(0, 1, At, B1); PG8_BAR; PG8_SCHED;
	s_setprio 1
	s_waitcnt lgkmcnt(0)
	v_mfma_f32_16x16x32_bf16 v[62:65], v[144:147], v[188:191], v[62:65]
	v_mfma_f32_16x16x32_bf16 v[62:65], v[160:163], v[206:209], v[62:65]
	v_mfma_f32_16x16x32_bf16 v[58:61], v[164:167], v[188:191], v[58:61]
	v_mfma_f32_16x16x32_bf16 v[58:61], v[168:171], v[206:209], v[58:61]
	v_mfma_f32_16x16x32_bf16 v[46:49], v[144:147], v[210:213], v[46:49]
	v_mfma_f32_16x16x32_bf16 v[46:49], v[160:163], v[214:217], v[46:49]
	v_mfma_f32_16x16x32_bf16 v[42:45], v[164:167], v[210:213], v[42:45]
	v_mfma_f32_16x16x32_bf16 v[42:45], v[168:171], v[214:217], v[42:45]
	v_mfma_f32_16x16x32_bf16 v[30:33], v[144:147], v[218:221], v[30:33]
	v_mfma_f32_16x16x32_bf16 v[30:33], v[160:163], v[222:225], v[30:33]
	v_mfma_f32_16x16x32_bf16 v[26:29], v[164:167], v[218:221], v[26:29]
	v_mfma_f32_16x16x32_bf16 v[26:29], v[168:171], v[222:225], v[26:29]
	v_mfma_f32_16x16x32_bf16 v[14:17], v[144:147], v[226:229], v[14:17]
	v_mfma_f32_16x16x32_bf16 v[14:17], v[160:163], v[230:233], v[14:17]
	v_mfma_f32_16x16x32_bf16 v[10:13], v[164:167], v[226:229], v[10:13]
	v_mfma_f32_16x16x32_bf16 v[10:13], v[168:171], v[230:233], v[10:13]
	s_setprio 0
	s_setprio 1
	v_mfma_f32_16x16x32_bf16 v[54:57], v[172:175], v[188:191], v[54:57]
	v_mfma_f32_16x16x32_bf16 v[54:57], v[176:179], v[206:209], v[54:57]
	v_mfma_f32_16x16x32_bf16 v[50:53], v[180:183], v[188:191], v[50:53]
	v_mfma_f32_16x16x32_bf16 v[50:53], v[184:187], v[206:209], v[50:53]
	v_mfma_f32_16x16x32_bf16 v[38:41], v[172:175], v[210:213], v[38:41]
	v_mfma_f32_16x16x32_bf16 v[38:41], v[176:179], v[214:217], v[38:41]
	v_mfma_f32_16x16x32_bf16 v[34:37], v[180:183], v[210:213], v[34:37]
	v_mfma_f32_16x16x32_bf16 v[34:37], v[184:187], v[214:217], v[34:37]
	v_mfma_f32_16x16x32_bf16 v[22:25], v[172:175], v[218:221], v[22:25]
	v_mfma_f32_16x16x32_bf16 v[22:25], v[176:179], v[222:225], v[22:25]
	v_mfma_f32_16x16x32_bf16 v[18:21], v[180:183], v[218:221], v[18:21]
	v_mfma_f32_16x16x32_bf16 v[18:21], v[184:187], v[222:225], v[18:21]
	v_mfma_f32_16x16x32_bf16 v[6:9], v[172:175], v[226:229], v[6:9]
	v_mfma_f32_16x16x32_bf16 v[6:9], v[176:179], v[230:233], v[6:9]
	v_mfma_f32_16x16x32_bf16 v[2:5], v[180:183], v[226:229], v[2:5]
	v_mfma_f32_16x16x32_bf16 v[2:5], v[184:187], v[230:233], v[2:5]
	s_setprio 0
	s_barrier
	s_add_i32 s72, 0, 0x18000
	v_add_u32_e32 v153, s72, v150
	s_add_i32 s73, 0, 0x1c000
	ds_read_b128 v[144:147], v153
	ds_read_b128 v[160:163], v153 offset:1024
	ds_read_b128 v[164:167], v153 offset:2048
	ds_read_b128 v[168:171], v153 offset:3072
	v_add_u32_e32 v153, s73, v150
	ds_read_b128 v[172:175], v153
	ds_read_b128 v[176:179], v153 offset:1024
	ds_read_b128 v[180:183], v153 offset:2048
	ds_read_b128 v[184:187], v153 offset:3072
	s_add_u32 s24, s46, 0x40000
	s_addc_u32 s25, s47, 0
	s_mov_b32 m0, s57
	v_lshl_add_u64 v[236:237], s[24:25], 0, v[130:131]
	ds_read_b128 v[188:191], v152 offset:32768
	ds_read_b128 v[206:209], v152 offset:33792
	ds_read_b128 v[210:213], v152 offset:34816
	ds_read_b128 v[214:217], v152 offset:35840
	ds_read_b128 v[218:221], v152 offset:36864
	ds_read_b128 v[222:225], v152 offset:37888
	ds_read_b128 v[226:229], v152 offset:38912
	ds_read_b128 v[230:233], v152 offset:39936
	global_load_lds_dwordx4 v[236:237], off
	v_lshl_add_u64 v[236:237], s[24:25], 0, v[134:135]
	s_mov_b32 m0, s58
	s_nop 0
	global_load_lds_dwordx4 v[236:237], off
	s_waitcnt vmcnt(8)
	s_waitcnt lgkmcnt(0)
	s_barrier
	s_setprio 1
	s_waitcnt lgkmcnt(0)
	v_mfma_f32_16x16x32_bf16 v[126:129], v[144:147], v[188:191], v[126:129]
	v_mfma_f32_16x16x32_bf16 v[126:129], v[160:163], v[206:209], v[126:129]
	v_mfma_f32_16x16x32_bf16 v[122:125], v[164:167], v[188:191], v[122:125]
	v_mfma_f32_16x16x32_bf16 v[122:125], v[168:171], v[206:209], v[122:125]
	v_mfma_f32_16x16x32_bf16 v[110:113], v[144:147], v[210:213], v[110:113]
	v_mfma_f32_16x16x32_bf16 v[110:113], v[160:163], v[214:217], v[110:113]
	v_mfma_f32_16x16x32_bf16 v[106:109], v[164:167], v[210:213], v[106:109]
	v_mfma_f32_16x16x32_bf16 v[106:109], v[168:171], v[214:217], v[106:109]
	v_mfma_f32_16x16x32_bf16 v[94:97], v[144:147], v[218:221], v[94:97]
	v_mfma_f32_16x16x32_bf16 v[94:97], v[160:163], v[222:225], v[94:97]
	v_mfma_f32_16x16x32_bf16 v[90:93], v[164:167], v[218:221], v[90:93]
	v_mfma_f32_16x16x32_bf16 v[90:93], v[168:171], v[222:225], v[90:93]
	v_mfma_f32_16x16x32_bf16 v[78:81], v[144:147], v[226:229], v[78:81]
	v_mfma_f32_16x16x32_bf16 v[78:81], v[160:163], v[230:233], v[78:81]
	v_mfma_f32_16x16x32_bf16 v[74:77], v[164:167], v[226:229], v[74:77]
	v_mfma_f32_16x16x32_bf16 v[74:77], v[168:171], v[230:233], v[74:77]
	s_setprio 0
	s_setprio 1
	v_mfma_f32_16x16x32_bf16 v[118:121], v[172:175], v[188:191], v[118:121]
	v_mfma_f32_16x16x32_bf16 v[118:121], v[176:179], v[206:209], v[118:121]
	v_mfma_f32_16x16x32_bf16 v[114:117], v[180:183], v[188:191], v[114:117]
	v_mfma_f32_16x16x32_bf16 v[114:117], v[184:187], v[206:209], v[114:117]
	v_mfma_f32_16x16x32_bf16 v[102:105], v[172:175], v[210:213], v[102:105]
	v_mfma_f32_16x16x32_bf16 v[102:105], v[176:179], v[214:217], v[102:105]
	v_mfma_f32_16x16x32_bf16 v[98:101], v[180:183], v[210:213], v[98:101]
	v_mfma_f32_16x16x32_bf16 v[98:101], v[184:187], v[214:217], v[98:101]
	v_mfma_f32_16x16x32_bf16 v[86:89], v[172:175], v[218:221], v[86:89]
	v_mfma_f32_16x16x32_bf16 v[86:89], v[176:179], v[222:225], v[86:89]
	v_mfma_f32_16x16x32_bf16 v[82:85], v[180:183], v[218:221], v[82:85]
	v_mfma_f32_16x16x32_bf16 v[82:85], v[184:187], v[222:225], v[82:85]
	v_mfma_f32_16x16x32_bf16 v[70:73], v[172:175], v[226:229], v[70:73]
	v_mfma_f32_16x16x32_bf16 v[70:73], v[176:179], v[230:233], v[70:73]
	v_mfma_f32_16x16x32_bf16 v[66:69], v[180:183], v[226:229], v[66:69]
	v_mfma_f32_16x16x32_bf16 v[66:69], v[184:187], v[230:233], v[66:69]
	s_setprio 0
	s_barrier
; #define PG8_STAGE(bufoff, gbase, voff) do { _Pragma("unroll") for (int _i = 0; _i < 2; ++_i) \
;         __builtin_amdgcn_global_load_lds((const unsigned*)((const char*)(gbase) + (voff)[_i]), (PG8_LAS unsigned*)(lds + (bufoff) + ldsw + _i * 8192), 16, 0, 0); } while (0)
; #define PG8_LDA(dst, b, h) do { _Pragma("unroll") for (int m = 0; m < 4; ++m) _Pragma("unroll") for (int k = 0; k < 2; ++k) dst[m][k] = *(const PG8_LAS bf16x8*)(lds + PG8_SA(b, h) + aoff + m * 2048 + k * 1024); } while (0)
; #define PG8_MMA(ai, bj, At, Bt) do { __builtin_amdgcn_s_setprio(1); _Pragma("unroll") for (int m = 0; m < 4; ++m) _Pragma("unroll") for (int n = 0; n < 2; ++n) _Pragma("unroll") for (int k = 0; k < 2; ++k) \
;         acc[ai][bj][m][n] = __builtin_amdgcn_mfma_f32_16x16x32_bf16(Bt[n][k], At[m][k], acc[ai][bj][m][n], 0, 0, 0); __builtin_amdgcn_s_setprio(0); } while (0)
; #define PG8_WAIT_V(n) asm volatile("s_waitcnt vmcnt(" #n ")" ::: "memory")
; #define PG8_WAIT_L(n) asm volatile("s_waitcnt lgkmcnt(" #n ")" ::: "memory")
; #define PG8_BAR __builtin_amdgcn_s_barrier()
; #define PG8_SCHED __builtin_amdgcn_sched_barrier(0)
; template <class Epi, class Sched, bool ALIGN_EPI = false, bool SP2 = false>
; __device__ __forceinline__ void gemm_phase(PG8_LAS unsigned char* lds, const Gemm g, const Sched& S, const Epi& E) {
;     ...
;             PG8_LDA(At, 1, 1); PG8_STAGE(PG8_SB(1, 0), b3, voffB); PG8_STAGE(PG8_SB(1, 1), b3 + hstep, voffB); PG8_STAGE(PG8_SA(1, 0), a3, voffA);
;             PG8_WAIT_V(8); PG8_WAIT_L(0); PG8_BAR; PG8_MMA(1, 0, At, B0); PG8_MMA(1, 1, At, B1); PG8_BAR; PG8_SCHED;
	s_add_i32 s24, s72, s51
	v_lshl_add_u64 v[148:149], v[148:149], 0, s[38:39]
	s_mov_b32 m0, s24
	ds_read_b128 v[188:191], v152 offset:49152
	ds_read_b128 v[206:209], v152 offset:50176
	ds_read_b128 v[210:213], v152 offset:51200
	ds_read_b128 v[214:217], v152 offset:52224
	ds_read_b128 v[218:221], v152 offset:53248
	ds_read_b128 v[222:225], v152 offset:54272
	ds_read_b128 v[226:229], v152 offset:55296
	ds_read_b128 v[230:233], v152 offset:56320
	global_load_lds_dwordx4 v[148:149], off
	s_add_i32 m0, s24, 0x2000
	s_add_u32 s24, s42, 0x40080
	v_lshl_add_u64 v[148:149], v[234:235], 0, s[38:39]
	s_addc_u32 s25, s43, 0
	s_add_i32 s42, s73, s51
	global_load_lds_dwordx4 v[148:149], off
	v_lshl_add_u64 v[148:149], s[24:25], 0, v[132:133]
	s_mov_b32 m0, s42
	s_nop 0
	global_load_lds_dwordx4 v[148:149], off
	v_lshl_add_u64 v[148:149], s[24:25], 0, v[136:137]
	s_add_i32 m0, s42, 0x2000
	s_nop 0
	global_load_lds_dwordx4 v[148:149], off
	v_lshl_add_u64 v[148:149], s[26:27], 0, v[130:131]
	s_mov_b32 m0, s64
	s_nop 0
	global_load_lds_dwordx4 v[148:149], off
	v_lshl_add_u64 v[148:149], s[26:27], 0, v[134:135]
	s_mov_b32 m0, s65
	s_nop 0
	global_load_lds_dwordx4 v[148:149], off
	s_waitcnt vmcnt(8)
	s_waitcnt lgkmcnt(0)
	s_barrier
	s_setprio 1
	s_waitcnt lgkmcnt(0)
	v_mfma_f32_16x16x32_bf16 v[62:65], v[144:147], v[188:191], v[62:65]
	v_mfma_f32_16x16x32_bf16 v[62:65], v[160:163], v[206:209], v[62:65]
	v_mfma_f32_16x16x32_bf16 v[58:61], v[164:167], v[188:191], v[58:61]
	v_mfma_f32_16x16x32_bf16 v[58:61], v[168:171], v[206:209], v[58:61]
	v_mfma_f32_16x16x32_bf16 v[46:49], v[144:147], v[210:213], v[46:49]
	v_mfma_f32_16x16x32_bf16 v[46:49], v[160:163], v[214:217], v[46:49]
	v_mfma_f32_16x16x32_bf16 v[42:45], v[164:167], v[210:213], v[42:45]
	v_mfma_f32_16x16x32_bf16 v[42:45], v[168:171], v[214:217], v[42:45]
	v_mfma_f32_16x16x32_bf16 v[30:33], v[144:147], v[218:221], v[30:33]
	v_mfma_f32_16x16x32_bf16 v[30:33], v[160:163], v[222:225], v[30:33]
	v_mfma_f32_16x16x32_bf16 v[26:29], v[164:167], v[218:221], v[26:29]
	v_mfma_f32_16x16x32_bf16 v[26:29], v[168:171], v[222:225], v[26:29]
	v_mfma_f32_16x16x32_bf16 v[14:17], v[144:147], v[226:229], v[14:17]
	v_mfma_f32_16x16x32_bf16 v[14:17], v[160:163], v[230:233], v[14:17]
	v_mfma_f32_16x16x32_bf16 v[10:13], v[164:167], v[226:229], v[10:13]
	v_mfma_f32_16x16x32_bf16 v[10:13], v[168:171], v[230:233], v[10:13]
	s_setprio 0
	s_setprio 1
	v_mfma_f32_16x16x32_bf16 v[54:57], v[172:175], v[188:191], v[54:57]
	v_mfma_f32_16x16x32_bf16 v[54:57], v[176:179], v[206:209], v[54:57]
	v_mfma_f32_16x16x32_bf16 v[50:53], v[180:183], v[188:191], v[50:53]
	v_mfma_f32_16x16x32_bf16 v[50:53], v[184:187], v[206:209], v[50:53]
	v_mfma_f32_16x16x32_bf16 v[38:41], v[172:175], v[210:213], v[38:41]
	v_mfma_f32_16x16x32_bf16 v[38:41], v[176:179], v[214:217], v[38:41]
	v_mfma_f32_16x16x32_bf16 v[34:37], v[180:183], v[210:213], v[34:37]
	v_mfma_f32_16x16x32_bf16 v[34:37], v[184:187], v[214:217], v[34:37]
	v_mfma_f32_16x16x32_bf16 v[22:25], v[172:175], v[218:221], v[22:25]
	v_mfma_f32_16x16x32_bf16 v[22:25], v[176:179], v[222:225], v[22:25]
	v_mfma_f32_16x16x32_bf16 v[18:21], v[180:183], v[218:221], v[18:21]
	v_mfma_f32_16x16x32_bf16 v[18:21], v[184:187], v[222:225], v[18:21]
	v_mfma_f32_16x16x32_bf16 v[6:9], v[172:175], v[226:229], v[6:9]
	v_mfma_f32_16x16x32_bf16 v[6:9], v[176:179], v[230:233], v[6:9]
	v_mfma_f32_16x16x32_bf16 v[2:5], v[180:183], v[226:229], v[2:5]
	v_mfma_f32_16x16x32_bf16 v[2:5], v[184:187], v[230:233], v[2:5]
	s_setprio 0
	s_barrier
	s_add_i32 s71, s71, 2
	s_add_u32 s69, s69, 0x100
	s_addc_u32 s70, s70, 0
	s_cmp_gt_u32 s71, 13
	s_mov_b64 s[24:25], s[2:3]
	s_cbranch_scc0 .LBB0_238
	s_and_b64 vcc, exec, s[6:7]
	s_cbranch_vccz .LBB0_241
	s_barrier

; #define PG8_STAGE(bufoff, gbase, voff) do { _Pragma("unroll") for (int _i = 0; _i < 2; ++_i) \
;         __builtin_amdgcn_global_load_lds((const unsigned*)((const char*)(gbase) + (voff)[_i]), (PG8_LAS unsigned*)(lds + (bufoff) + ldsw + _i * 8192), 16, 0, 0); } while (0)
; #define PG8_LDA(dst, b, h) do { _Pragma("unroll") for (int m = 0; m < 4; ++m) _Pragma("unroll") for (int k = 0; k < 2; ++k) dst[m][k] = *(const PG8_LAS bf16x8*)(lds + PG8_SA(b, h) + aoff + m * 2048 + k * 1024); } while (0)
; #define PG8_LDB(dst, b, h) do { _Pragma("unroll") for (int n = 0; n < 2; ++n) _Pragma("unroll") for (int k = 0; k < 2; ++k) dst[n][k] = *(const PG8_LAS bf16x8*)(lds + PG8_SB(b, h) + boff + n * 2048 + k * 1024); } while (0)
; #define PG8_MMA(ai, bj, At, Bt) do { __builtin_amdgcn_s_setprio(1); _Pragma("unroll") for (int m = 0; m < 4; ++m) _Pragma("unroll") for (int n = 0; n < 2; ++n) _Pragma("unroll") for (int k = 0; k < 2; ++k) \
;         acc[ai][bj][m][n] = __builtin_amdgcn_mfma_f32_16x16x32_bf16(Bt[n][k], At[m][k], acc[ai][bj][m][n], 0, 0, 0); __builtin_amdgcn_s_setprio(0); } while (0)
; #define PG8_WAIT_V(n) asm volatile("s_waitcnt vmcnt(" #n ")" ::: "memory")
; #define PG8_WAIT_L(n) asm volatile("s_waitcnt lgkmcnt(" #n ")" ::: "memory")
; template <class Epi, class Sched, bool ALIGN_EPI = false, bool SP2 = false>
; __device__ __forceinline__ void gemm_phase(PG8_LAS unsigned char* lds, const Gemm g, const Sched& S, const Epi& E) {
;     ...
;             const bool last = (t == nt - 2);
;             const char* a1 = cA + (size_t)(t + 1) * kstepA;
;             const char* a2 = last ? nA : cA + (size_t)(t + 2) * kstepA; const char* b2 = last ? nB : cB + (size_t)(t + 2) * kstep;
;             const char* a3 = a2 + kstepA; const char* b3 = b2 + kstep;
;             if (last && has_next) S.a_ready(nxt);
;             if constexpr (SP2) {
;             PG8_LDB(B0, 0, 0); PG8_LDB(B1, 0, 1); PG8_SCHED; PG8_LDA(At, 0, 0); PG8_STAGE(PG8_SA(1, 1), a1 + hstep, voffA);
;             PG8_WAIT_V(8); PG8_WAIT_L(0); PG8_BAR; PG8_MMA(0, 0, At, B0); PG8_MMA(0, 1, At, B1); PG8_BAR; PG8_SCHED;
;             PG8_LDA(At, 0, 1); PG8_STAGE(PG8_SB(0, 0), b2, voffB); PG8_STAGE(PG8_SB(0, 1), b2 + hstep, voffB); PG8_STAGE(PG8_SA(0, 0), a2, voffA);
;             PG8_WAIT_V(8); PG8_WAIT_L(0); PG8_BAR; PG8_MMA(1, 0, At, B0); PG8_MMA(1, 1, At, B1); PG8_BAR; PG8_SCHED;
.LBB0_310:
	s_add_i32 s49, s24, 2
	s_add_u32 s25, s2, 0x4000
	s_addc_u32 s26, s3, 0
	s_cmp_eq_u32 s59, s24
	s_cselect_b32 s27, s9, s26
	s_cselect_b32 s26, s8, s25
	s_cselect_b32 s66, s44, s47
	s_cselect_b32 s67, s45, s48
	s_add_u32 s24, s26, 0x4000
	s_addc_u32 s25, s27, 0
	s_add_i32 s65, 0, 0x14000
	v_add_u32_e32 v142, s76, v187
	v_add_u32_e32 v167, s65, v187
	ds_read_b128 v[130:133], v142
	ds_read_b128 v[134:137], v142 offset:1024
	ds_read_b128 v[138:141], v142 offset:2048
	ds_read_b128 v[142:145], v142 offset:3072
	ds_read_b128 v[146:149], v167
	ds_read_b128 v[150:153], v167 offset:1024
	ds_read_b128 v[206:209], v167 offset:2048
	ds_read_b128 v[210:213], v167 offset:3072
	v_lshl_add_u64 v[184:185], s[2:3], 0, v[182:183]
	s_add_i32 m0, s51, 0xc000
	ds_read_b128 v[214:217], v188
	ds_read_b128 v[218:221], v188 offset:1024
	ds_read_b128 v[222:225], v188 offset:2048
	ds_read_b128 v[226:229], v188 offset:3072
	ds_read_b128 v[230:233], v188 offset:4096
	ds_read_b128 v[234:237], v188 offset:5120
	ds_read_b128 v[238:241], v188 offset:6144
	ds_read_b128 v[242:245], v188 offset:7168
	global_load_lds_dwordx4 v[184:185], off
	v_lshl_add_u64 v[184:185], s[2:3], 0, v[180:181]
	s_add_i32 m0, s51, 0xe000
	s_nop 0
	global_load_lds_dwordx4 v[184:185], off
	s_waitcnt vmcnt(8)
	s_waitcnt lgkmcnt(0)
	s_barrier
	s_setprio 1
	s_waitcnt lgkmcnt(0)
	v_mfma_f32_16x16x32_bf16 v[126:129], v[130:133], v[214:217], v[126:129]
	v_mfma_f32_16x16x32_bf16 v[126:129], v[134:137], v[218:221], v[126:129]
	v_mfma_f32_16x16x32_bf16 v[122:125], v[138:141], v[214:217], v[122:125]
	v_mfma_f32_16x16x32_bf16 v[122:125], v[142:145], v[218:221], v[122:125]
	v_mfma_f32_16x16x32_bf16 v[110:113], v[130:133], v[222:225], v[110:113]
	v_mfma_f32_16x16x32_bf16 v[110:113], v[134:137], v[226:229], v[110:113]
	v_mfma_f32_16x16x32_bf16 v[106:109], v[138:141], v[222:225], v[106:109]
	v_mfma_f32_16x16x32_bf16 v[106:109], v[142:145], v[226:229], v[106:109]
	v_mfma_f32_16x16x32_bf16 v[94:97], v[130:133], v[230:233], v[94:97]
	v_mfma_f32_16x16x32_bf16 v[94:97], v[134:137], v[234:237], v[94:97]
	v_mfma_f32_16x16x32_bf16 v[90:93], v[138:141], v[230:233], v[90:93]
	v_mfma_f32_16x16x32_bf16 v[90:93], v[142:145], v[234:237], v[90:93]
	v_mfma_f32_16x16x32_bf16 v[78:81], v[130:133], v[238:241], v[78:81]
	v_mfma_f32_16x16x32_bf16 v[78:81], v[134:137], v[242:245], v[78:81]
	v_mfma_f32_16x16x32_bf16 v[74:77], v[138:141], v[238:241], v[74:77]
	v_mfma_f32_16x16x32_bf16 v[74:77], v[142:145], v[242:245], v[74:77]
	s_setprio 0
	s_setprio 1
	v_mfma_f32_16x16x32_bf16 v[118:121], v[146:149], v[214:217], v[118:121]
	v_mfma_f32_16x16x32_bf16 v[118:121], v[150:153], v[218:221], v[118:121]
	v_mfma_f32_16x16x32_bf16 v[114:117], v[206:209], v[214:217], v[114:117]
	v_mfma_f32_16x16x32_bf16 v[114:117], v[210:213], v[218:221], v[114:117]
	v_mfma_f32_16x16x32_bf16 v[102:105], v[146:149], v[222:225], v[102:105]
	v_mfma_f32_16x16x32_bf16 v[102:105], v[150:153], v[226:229], v[102:105]
	v_mfma_f32_16x16x32_bf16 v[98:101], v[206:209], v[222:225], v[98:101]
	v_mfma_f32_16x16x32_bf16 v[98:101], v[210:213], v[226:229], v[98:101]
	v_mfma_f32_16x16x32_bf16 v[86:89], v[146:149], v[230:233], v[86:89]
	v_mfma_f32_16x16x32_bf16 v[86:89], v[150:153], v[234:237], v[86:89]
	v_mfma_f32_16x16x32_bf16 v[82:85], v[206:209], v[230:233], v[82:85]
	v_mfma_f32_16x16x32_bf16 v[82:85], v[210:213], v[234:237], v[82:85]
	v_mfma_f32_16x16x32_bf16 v[70:73], v[146:149], v[238:241], v[70:73]
	v_mfma_f32_16x16x32_bf16 v[70:73], v[150:153], v[242:245], v[70:73]
	v_mfma_f32_16x16x32_bf16 v[66:69], v[206:209], v[238:241], v[66:69]
	v_mfma_f32_16x16x32_bf16 v[66:69], v[210:213], v[242:245], v[66:69]
	s_setprio 0
	s_barrier
	s_add_i32 s68, s76, s50
	v_lshl_add_u64 v[184:185], s[66:67], 0, v[0:1]
	s_mov_b32 m0, s68
	ds_read_b128 v[214:217], v188 offset:16384
	ds_read_b128 v[218:221], v188 offset:17408
	ds_read_b128 v[222:225], v188 offset:18432
	ds_read_b128 v[226:229], v188 offset:19456
	ds_read_b128 v[230:233], v188 offset:20480
	ds_read_b128 v[234:237], v188 offset:21504
	ds_read_b128 v[238:241], v188 offset:22528
	ds_read_b128 v[242:245], v188 offset:23552
	global_load_lds_dwordx4 v[184:185], off
	s_add_i32 m0, s68, 0x2000
	v_lshl_add_u64 v[190:191], s[66:67], 0, v[164:165]
	s_add_u32 s66, s66, s12
	s_addc_u32 s67, s67, 0
	s_add_i32 s65, s65, s50
	global_load_lds_dwordx4 v[190:191], off
	v_lshl_add_u64 v[246:247], s[66:67], 0, v[0:1]
	s_mov_b32 m0, s65
	v_lshl_add_u64 v[248:249], s[66:67], 0, v[164:165]
	global_load_lds_dwordx4 v[246:247], off
	s_add_i32 m0, s65, 0x2000
	v_lshl_add_u64 v[250:251], s[26:27], 0, v[160:161]
	global_load_lds_dwordx4 v[248:249], off
	s_mov_b32 m0, s51
	s_nop 0
	global_load_lds_dwordx4 v[250:251], off
	v_lshl_add_u64 v[250:251], s[26:27], 0, v[162:163]
	s_mov_b32 m0, s52
	s_nop 0
	global_load_lds_dwordx4 v[250:251], off
	s_waitcnt vmcnt(8)
	s_waitcnt lgkmcnt(0)
	s_barrier
; #define PG8_STAGE(bufoff, gbase, voff) do { _Pragma("unroll") for (int _i = 0; _i < 2; ++_i) \
;         __builtin_amdgcn_global_load_lds((const unsigned*)((const char*)(gbase) + (voff)[_i]), (PG8_LAS unsigned*)(lds + (bufoff) + ldsw + _i * 8192), 16, 0, 0); } while (0)
; #define PG8_LDA(dst, b, h) do { _Pragma("unroll") for (int m = 0; m < 4; ++m) _Pragma("unroll") for (int k = 0; k < 2; ++k) dst[m][k] = *(const PG8_LAS bf16x8*)(lds + PG8_SA(b, h) + aoff + m * 2048 + k * 1024); } while (0)
; #define PG8_LDB(dst, b, h) do { _Pragma("unroll") for (int n = 0; n < 2; ++n) _Pragma("unroll") for (int k = 0; k < 2; ++k) dst[n][k] = *(const PG8_LAS bf16x8*)(lds + PG8_SB(b, h) + boff + n * 2048 + k * 1024); } while (0)
; #define PG8_MMA(ai, bj, At, Bt) do { __builtin_amdgcn_s_setprio(1); _Pragma("unroll") for (int m = 0; m < 4; ++m) _Pragma("unroll") for (int n = 0; n < 2; ++n) _Pragma("unroll") for (int k = 0; k < 2; ++k) \
;         acc[ai][bj][m][n] = __builtin_amdgcn_mfma_f32_16x16x32_bf16(Bt[n][k], At[m][k], acc[ai][bj][m][n], 0, 0, 0); __builtin_amdgcn_s_setprio(0); } while (0)
; #define PG8_WAIT_V(n) asm volatile("s_waitcnt vmcnt(" #n ")" ::: "memory")
; #define PG8_WAIT_L(n) asm volatile("s_waitcnt lgkmcnt(" #n ")" ::: "memory")
; #define PG8_BAR __builtin_amdgcn_s_barrier()
; #define PG8_SCHED __builtin_amdgcn_sched_barrier(0)
; template <class Epi, class Sched, bool ALIGN_EPI = false, bool SP2 = false>
; __device__ __forceinline__ void gemm_phase(PG8_LAS unsigned char* lds, const Gemm g, const Sched& S, const Epi& E) {
;     ...
;             PG8_WAIT_V(8); PG8_WAIT_L(0); PG8_BAR; PG8_MMA(1, 0, At, B0); PG8_MMA(1, 1, At, B1); PG8_BAR; PG8_SCHED;
;             PG8_LDB(B0, 1, 0); PG8_LDB(B1, 1, 1); PG8_SCHED; PG8_LDA(At, 1, 0); PG8_STAGE(PG8_SA(0, 1), a2 + hstep, voffA);
;             PG8_WAIT_V(8); PG8_WAIT_L(0); PG8_BAR; PG8_MMA(0, 0, At, B0); PG8_MMA(0, 1, At, B1); PG8_BAR; PG8_SCHED;
	s_setprio 1
	s_waitcnt lgkmcnt(0)
	v_mfma_f32_16x16x32_bf16 v[62:65], v[130:133], v[214:217], v[62:65]
	v_mfma_f32_16x16x32_bf16 v[62:65], v[134:137], v[218:221], v[62:65]
	v_mfma_f32_16x16x32_bf16 v[58:61], v[138:141], v[214:217], v[58:61]
	v_mfma_f32_16x16x32_bf16 v[58:61], v[142:145], v[218:221], v[58:61]
	v_mfma_f32_16x16x32_bf16 v[46:49], v[130:133], v[222:225], v[46:49]
	v_mfma_f32_16x16x32_bf16 v[46:49], v[134:137], v[226:229], v[46:49]
	v_mfma_f32_16x16x32_bf16 v[42:45], v[138:141], v[222:225], v[42:45]
	v_mfma_f32_16x16x32_bf16 v[42:45], v[142:145], v[226:229], v[42:45]
	v_mfma_f32_16x16x32_bf16 v[30:33], v[130:133], v[230:233], v[30:33]
	v_mfma_f32_16x16x32_bf16 v[30:33], v[134:137], v[234:237], v[30:33]
	v_mfma_f32_16x16x32_bf16 v[26:29], v[138:141], v[230:233], v[26:29]
	v_mfma_f32_16x16x32_bf16 v[26:29], v[142:145], v[234:237], v[26:29]
	v_mfma_f32_16x16x32_bf16 v[14:17], v[130:133], v[238:241], v[14:17]
	v_mfma_f32_16x16x32_bf16 v[14:17], v[134:137], v[242:245], v[14:17]
	v_mfma_f32_16x16x32_bf16 v[10:13], v[138:141], v[238:241], v[10:13]
	v_mfma_f32_16x16x32_bf16 v[10:13], v[142:145], v[242:245], v[10:13]
	s_setprio 0
	s_setprio 1
	v_mfma_f32_16x16x32_bf16 v[54:57], v[146:149], v[214:217], v[54:57]
	v_mfma_f32_16x16x32_bf16 v[54:57], v[150:153], v[218:221], v[54:57]
	v_mfma_f32_16x16x32_bf16 v[50:53], v[206:209], v[214:217], v[50:53]
	v_mfma_f32_16x16x32_bf16 v[50:53], v[210:213], v[218:221], v[50:53]
	v_mfma_f32_16x16x32_bf16 v[38:41], v[146:149], v[222:225], v[38:41]
	v_mfma_f32_16x16x32_bf16 v[38:41], v[150:153], v[226:229], v[38:41]
	v_mfma_f32_16x16x32_bf16 v[34:37], v[206:209], v[222:225], v[34:37]
	v_mfma_f32_16x16x32_bf16 v[34:37], v[210:213], v[226:229], v[34:37]
	v_mfma_f32_16x16x32_bf16 v[22:25], v[146:149], v[230:233], v[22:25]
	v_mfma_f32_16x16x32_bf16 v[22:25], v[150:153], v[234:237], v[22:25]
	v_mfma_f32_16x16x32_bf16 v[18:21], v[206:209], v[230:233], v[18:21]
	v_mfma_f32_16x16x32_bf16 v[18:21], v[210:213], v[234:237], v[18:21]
	v_mfma_f32_16x16x32_bf16 v[6:9], v[146:149], v[238:241], v[6:9]
	v_mfma_f32_16x16x32_bf16 v[6:9], v[150:153], v[242:245], v[6:9]
	v_mfma_f32_16x16x32_bf16 v[2:5], v[206:209], v[238:241], v[2:5]
	v_mfma_f32_16x16x32_bf16 v[2:5], v[210:213], v[242:245], v[2:5]
	s_setprio 0
	s_barrier
	s_add_i32 s65, 0, 0x18000
	s_add_i32 s66, 0, 0x1c000
	v_add_u32_e32 v142, s65, v187
	v_add_u32_e32 v167, s66, v187
	ds_read_b128 v[130:133], v142
	ds_read_b128 v[134:137], v142 offset:1024
	ds_read_b128 v[138:141], v142 offset:2048
	ds_read_b128 v[142:145], v142 offset:3072
	ds_read_b128 v[146:149], v167
	ds_read_b128 v[150:153], v167 offset:1024
	ds_read_b128 v[206:209], v167 offset:2048
	ds_read_b128 v[210:213], v167 offset:3072
	s_add_u32 s26, s26, s12
	s_addc_u32 s27, s27, 0
	s_mov_b32 m0, s53
	v_lshl_add_u64 v[250:251], s[26:27], 0, v[160:161]
	ds_read_b128 v[214:217], v188 offset:32768
	ds_read_b128 v[218:221], v188 offset:33792
	ds_read_b128 v[222:225], v188 offset:34816
	ds_read_b128 v[226:229], v188 offset:35840
	ds_read_b128 v[230:233], v188 offset:36864
	ds_read_b128 v[234:237], v188 offset:37888
	ds_read_b128 v[238:241], v188 offset:38912
	ds_read_b128 v[242:245], v188 offset:39936
	global_load_lds_dwordx4 v[250:251], off
	v_lshl_add_u64 v[250:251], s[26:27], 0, v[162:163]
	s_mov_b32 m0, s54
	s_nop 0
	global_load_lds_dwordx4 v[250:251], off
	s_waitcnt vmcnt(8)
	s_waitcnt lgkmcnt(0)
	s_barrier
	s_setprio 1
	s_waitcnt lgkmcnt(0)
	v_mfma_f32_16x16x32_bf16 v[126:129], v[130:133], v[214:217], v[126:129]
	v_mfma_f32_16x16x32_bf16 v[126:129], v[134:137], v[218:221], v[126:129]
	v_mfma_f32_16x16x32_bf16 v[122:125], v[138:141], v[214:217], v[122:125]
	v_mfma_f32_16x16x32_bf16 v[122:125], v[142:145], v[218:221], v[122:125]
	v_mfma_f32_16x16x32_bf16 v[110:113], v[130:133], v[222:225], v[110:113]
	v_mfma_f32_16x16x32_bf16 v[110:113], v[134:137], v[226:229], v[110:113]
	v_mfma_f32_16x16x32_bf16 v[106:109], v[138:141], v[222:225], v[106:109]
	v_mfma_f32_16x16x32_bf16 v[106:109], v[142:145], v[226:229], v[106:109]
	v_mfma_f32_16x16x32_bf16 v[94:97], v[130:133], v[230:233], v[94:97]
	v_mfma_f32_16x16x32_bf16 v[94:97], v[134:137], v[234:237], v[94:97]
	v_mfma_f32_16x16x32_bf16 v[90:93], v[138:141], v[230:233], v[90:93]
	v_mfma_f32_16x16x32_bf16 v[90:93], v[142:145], v[234:237], v[90:93]
	v_mfma_f32_16x16x32_bf16 v[78:81], v[130:133], v[238:241], v[78:81]
	v_mfma_f32_16x16x32_bf16 v[78:81], v[134:137], v[242:245], v[78:81]
	v_mfma_f32_16x16x32_bf16 v[74:77], v[138:141], v[238:241], v[74:77]
	v_mfma_f32_16x16x32_bf16 v[74:77], v[142:145], v[242:245], v[74:77]
	s_setprio 0
	s_setprio 1
	v_mfma_f32_16x16x32_bf16 v[118:121], v[146:149], v[214:217], v[118:121]
	v_mfma_f32_16x16x32_bf16 v[118:121], v[150:153], v[218:221], v[118:121]
	v_mfma_f32_16x16x32_bf16 v[114:117], v[206:209], v[214:217], v[114:117]
	v_mfma_f32_16x16x32_bf16 v[114:117], v[210:213], v[218:221], v[114:117]
	v_mfma_f32_16x16x32_bf16 v[102:105], v[146:149], v[222:225], v[102:105]
	v_mfma_f32_16x16x32_bf16 v[102:105], v[150:153], v[226:229], v[102:105]
	v_mfma_f32_16x16x32_bf16 v[98:101], v[206:209], v[222:225], v[98:101]
	v_mfma_f32_16x16x32_bf16 v[98:101], v[210:213], v[226:229], v[98:101]
	v_mfma_f32_16x16x32_bf16 v[86:89], v[146:149], v[230:233], v[86:89]
	v_mfma_f32_16x16x32_bf16 v[86:89], v[150:153], v[234:237], v[86:89]
	v_mfma_f32_16x16x32_bf16 v[82:85], v[206:209], v[230:233], v[82:85]
	v_mfma_f32_16x16x32_bf16 v[82:85], v[210:213], v[234:237], v[82:85]
	v_mfma_f32_16x16x32_bf16 v[70:73], v[146:149], v[238:241], v[70:73]
	v_mfma_f32_16x16x32_bf16 v[70:73], v[150:153], v[242:245], v[70:73]
	v_mfma_f32_16x16x32_bf16 v[66:69], v[206:209], v[238:241], v[66:69]
	v_mfma_f32_16x16x32_bf16 v[66:69], v[210:213], v[242:245], v[66:69]
	s_setprio 0
	s_barrier
; #define PG8_STAGE(bufoff, gbase, voff) do { _Pragma("unroll") for (int _i = 0; _i < 2; ++_i) \
;         __builtin_amdgcn_global_load_lds((const unsigned*)((const char*)(gbase) + (voff)[_i]), (PG8_LAS unsigned*)(lds + (bufoff) + ldsw + _i * 8192), 16, 0, 0); } while (0)
; #define PG8_LDA(dst, b, h) do { _Pragma("unroll") for (int m = 0; m < 4; ++m) _Pragma("unroll") for (int k = 0; k < 2; ++k) dst[m][k] = *(const PG8_LAS bf16x8*)(lds + PG8_SA(b, h) + aoff + m * 2048 + k * 1024); } while (0)
; #define PG8_MMA(ai, bj, At, Bt) do { __builtin_amdgcn_s_setprio(1); _Pragma("unroll") for (int m = 0; m < 4; ++m) _Pragma("unroll") for (int n = 0; n < 2; ++n) _Pragma("unroll") for (int k = 0; k < 2; ++k) \
;         acc[ai][bj][m][n] = __builtin_amdgcn_mfma_f32_16x16x32_bf16(Bt[n][k], At[m][k], acc[ai][bj][m][n], 0, 0, 0); __builtin_amdgcn_s_setprio(0); } while (0)
; #define PG8_WAIT_V(n) asm volatile("s_waitcnt vmcnt(" #n ")" ::: "memory")
; #define PG8_WAIT_L(n) asm volatile("s_waitcnt lgkmcnt(" #n ")" ::: "memory")
; #define PG8_BAR __builtin_amdgcn_s_barrier()
; #define PG8_SCHED __builtin_amdgcn_sched_barrier(0)
; template <class Epi, class Sched, bool ALIGN_EPI = false, bool SP2 = false>
; __device__ __forceinline__ void gemm_phase(PG8_LAS unsigned char* lds, const Gemm g, const Sched& S, const Epi& E) {
;     ...
;             PG8_LDA(At, 1, 1); PG8_STAGE(PG8_SB(1, 0), b3, voffB); PG8_STAGE(PG8_SB(1, 1), b3 + hstep, voffB); PG8_STAGE(PG8_SA(1, 0), a3, voffA);
;             PG8_WAIT_V(8); PG8_WAIT_L(0); PG8_BAR; PG8_MMA(1, 0, At, B0); PG8_MMA(1, 1, At, B1); PG8_BAR; PG8_SCHED;
	s_add_i32 s26, s65, s50
	v_lshl_add_u64 v[184:185], v[184:185], 0, s[38:39]
	s_mov_b32 m0, s26
	ds_read_b128 v[214:217], v188 offset:49152
	ds_read_b128 v[218:221], v188 offset:50176
	ds_read_b128 v[222:225], v188 offset:51200
	ds_read_b128 v[226:229], v188 offset:52224
	ds_read_b128 v[230:233], v188 offset:53248
	ds_read_b128 v[234:237], v188 offset:54272
	ds_read_b128 v[238:241], v188 offset:55296
	ds_read_b128 v[242:245], v188 offset:56320
	global_load_lds_dwordx4 v[184:185], off
	v_lshl_add_u64 v[184:185], v[190:191], 0, s[38:39]
	s_add_i32 m0, s26, 0x2000
	s_add_i32 s26, s66, s50
	global_load_lds_dwordx4 v[184:185], off
	v_lshl_add_u64 v[184:185], v[246:247], 0, s[38:39]
	s_mov_b32 m0, s26
	s_nop 0
	global_load_lds_dwordx4 v[184:185], off
	v_lshl_add_u64 v[184:185], v[248:249], 0, s[38:39]
	s_add_i32 m0, s26, 0x2000
	s_nop 0
	global_load_lds_dwordx4 v[184:185], off
	v_lshl_add_u64 v[184:185], s[24:25], 0, v[160:161]
	s_mov_b32 m0, s56
	s_nop 0
	global_load_lds_dwordx4 v[184:185], off
	v_lshl_add_u64 v[184:185], s[24:25], 0, v[162:163]
	s_mov_b32 m0, s57
	s_nop 0
	global_load_lds_dwordx4 v[184:185], off
	s_waitcnt vmcnt(8)
	s_waitcnt lgkmcnt(0)
	s_barrier
	s_setprio 1
	s_waitcnt lgkmcnt(0)
	v_mfma_f32_16x16x32_bf16 v[62:65], v[130:133], v[214:217], v[62:65]
	v_mfma_f32_16x16x32_bf16 v[62:65], v[134:137], v[218:221], v[62:65]
	v_mfma_f32_16x16x32_bf16 v[58:61], v[138:141], v[214:217], v[58:61]
	v_mfma_f32_16x16x32_bf16 v[58:61], v[142:145], v[218:221], v[58:61]
	v_mfma_f32_16x16x32_bf16 v[46:49], v[130:133], v[222:225], v[46:49]
	v_mfma_f32_16x16x32_bf16 v[46:49], v[134:137], v[226:229], v[46:49]
	v_mfma_f32_16x16x32_bf16 v[42:45], v[138:141], v[222:225], v[42:45]
	v_mfma_f32_16x16x32_bf16 v[42:45], v[142:145], v[226:229], v[42:45]
	v_mfma_f32_16x16x32_bf16 v[30:33], v[130:133], v[230:233], v[30:33]
	v_mfma_f32_16x16x32_bf16 v[30:33], v[134:137], v[234:237], v[30:33]
	v_mfma_f32_16x16x32_bf16 v[26:29], v[138:141], v[230:233], v[26:29]
	v_mfma_f32_16x16x32_bf16 v[26:29], v[142:145], v[234:237], v[26:29]
	v_mfma_f32_16x16x32_bf16 v[14:17], v[130:133], v[238:241], v[14:17]
	v_mfma_f32_16x16x32_bf16 v[14:17], v[134:137], v[242:245], v[14:17]
	v_mfma_f32_16x16x32_bf16 v[10:13], v[138:141], v[238:241], v[10:13]
	v_mfma_f32_16x16x32_bf16 v[10:13], v[142:145], v[242:245], v[10:13]
	s_setprio 0
	s_setprio 1
	v_mfma_f32_16x16x32_bf16 v[54:57], v[146:149], v[214:217], v[54:57]
	v_mfma_f32_16x16x32_bf16 v[54:57], v[150:153], v[218:221], v[54:57]
	v_mfma_f32_16x16x32_bf16 v[50:53], v[206:209], v[214:217], v[50:53]
	v_mfma_f32_16x16x32_bf16 v[50:53], v[210:213], v[218:221], v[50:53]
	v_mfma_f32_16x16x32_bf16 v[38:41], v[146:149], v[222:225], v[38:41]
	v_mfma_f32_16x16x32_bf16 v[38:41], v[150:153], v[226:229], v[38:41]
	v_mfma_f32_16x16x32_bf16 v[34:37], v[206:209], v[222:225], v[34:37]
	v_mfma_f32_16x16x32_bf16 v[34:37], v[210:213], v[226:229], v[34:37]
	v_mfma_f32_16x16x32_bf16 v[22:25], v[146:149], v[230:233], v[22:25]
	v_mfma_f32_16x16x32_bf16 v[22:25], v[150:153], v[234:237], v[22:25]
	v_mfma_f32_16x16x32_bf16 v[18:21], v[206:209], v[230:233], v[18:21]
	v_mfma_f32_16x16x32_bf16 v[18:21], v[210:213], v[234:237], v[18:21]
	v_mfma_f32_16x16x32_bf16 v[6:9], v[146:149], v[238:241], v[6:9]
	v_mfma_f32_16x16x32_bf16 v[6:9], v[150:153], v[242:245], v[6:9]
	v_mfma_f32_16x16x32_bf16 v[2:5], v[206:209], v[238:241], v[2:5]
	v_mfma_f32_16x16x32_bf16 v[2:5], v[210:213], v[242:245], v[2:5]
	s_setprio 0
	s_barrier
	s_add_u32 s47, s47, 0x100
	s_addc_u32 s48, s48, 0
	s_add_u32 s2, s2, 0x8000
	s_addc_u32 s3, s3, 0
	s_cmp_ge_u32 s49, s55
	s_mov_b32 s24, s49
	s_cbranch_scc0 .LBB0_310
	s_and_b64 vcc, exec, s[42:43]
	s_cbranch_vccz .LBB0_313
	s_barrier

; #define PG8_STAGE(bufoff, gbase, voff) do { _Pragma("unroll") for (int _i = 0; _i < 2; ++_i) \
;         __builtin_amdgcn_global_load_lds((const unsigned*)((const char*)(gbase) + (voff)[_i]), (PG8_LAS unsigned*)(lds + (bufoff) + ldsw + _i * 8192), 16, 0, 0); } while (0)
; #define PG8_LDA(dst, b, h) do { _Pragma("unroll") for (int m = 0; m < 4; ++m) _Pragma("unroll") for (int k = 0; k < 2; ++k) dst[m][k] = *(const PG8_LAS bf16x8*)(lds + PG8_SA(b, h) + aoff + m * 2048 + k * 1024); } while (0)
; #define PG8_LDB(dst, b, h) do { _Pragma("unroll") for (int n = 0; n < 2; ++n) _Pragma("unroll") for (int k = 0; k < 2; ++k) dst[n][k] = *(const PG8_LAS bf16x8*)(lds + PG8_SB(b, h) + boff + n * 2048 + k * 1024); } while (0)
; #define PG8_MMA(ai, bj, At, Bt) do { __builtin_amdgcn_s_setprio(1); _Pragma("unroll") for (int m = 0; m < 4; ++m) _Pragma("unroll") for (int n = 0; n < 2; ++n) _Pragma("unroll") for (int k = 0; k < 2; ++k) \
;         acc[ai][bj][m][n] = __builtin_amdgcn_mfma_f32_16x16x32_bf16(Bt[n][k], At[m][k], acc[ai][bj][m][n], 0, 0, 0); __builtin_amdgcn_s_setprio(0); } while (0)
; #define PG8_WAIT_V(n) asm volatile("s_waitcnt vmcnt(" #n ")" ::: "memory")
; #define PG8_WAIT_L(n) asm volatile("s_waitcnt lgkmcnt(" #n ")" ::: "memory")
; template <class Epi, class Sched, bool ALIGN_EPI = false, bool SP2 = false>
; __device__ __forceinline__ void gemm_phase(PG8_LAS unsigned char* lds, const Gemm g, const Sched& S, const Epi& E) {
;     ...
;             const bool last = (t == nt - 2);
;             const char* a1 = cA + (size_t)(t + 1) * kstepA;
;             const char* a2 = last ? nA : cA + (size_t)(t + 2) * kstepA; const char* b2 = last ? nB : cB + (size_t)(t + 2) * kstep;
;             const char* a3 = a2 + kstepA; const char* b3 = b2 + kstep;
;             if (last && has_next) S.a_ready(nxt);
;             if constexpr (SP2) {
;             PG8_LDB(B0, 0, 0); PG8_LDB(B1, 0, 1); PG8_SCHED; PG8_LDA(At, 0, 0); PG8_STAGE(PG8_SA(1, 1), a1 + hstep, voffA);
;             PG8_WAIT_V(8); PG8_WAIT_L(0); PG8_BAR; PG8_MMA(0, 0, At, B0); PG8_MMA(0, 1, At, B1); PG8_BAR; PG8_SCHED;
;             PG8_LDA(At, 0, 1); PG8_STAGE(PG8_SB(0, 0), b2, voffB); PG8_STAGE(PG8_SB(0, 1), b2 + hstep, voffB); PG8_STAGE(PG8_SA(0, 0), a2, voffA);
;             PG8_WAIT_V(8); PG8_WAIT_L(0); PG8_BAR; PG8_MMA(1, 0, At, B0); PG8_MMA(1, 1, At, B1); PG8_BAR; PG8_SCHED;
.LBB0_409:
	s_add_u32 s24, s22, 0x8000
	s_addc_u32 s25, s23, 0
	s_cmp_eq_u32 s57, 12
	s_cselect_b32 s42, s53, s24
	s_cselect_b32 s43, s11, s25
	s_cselect_b32 s40, s54, s55
	s_cselect_b32 s41, s9, s56
	s_add_u32 s26, s42, 0x4000
	s_addc_u32 s27, s43, 0
	v_add_u32_e32 v145, s76, v142
	s_add_i32 s58, 0, 0x14000
	ds_read_b128 v[146:149], v145
	ds_read_b128 v[150:153], v145 offset:1024
	ds_read_b128 v[160:163], v145 offset:2048
	ds_read_b128 v[164:167], v145 offset:3072
	v_add_u32_e32 v145, s58, v142
	ds_read_b128 v[168:171], v145
	ds_read_b128 v[172:175], v145 offset:1024
	ds_read_b128 v[176:179], v145 offset:2048
	ds_read_b128 v[180:183], v145 offset:3072
	v_lshl_add_u64 v[230:231], s[22:23], 0, v[140:141]
	s_add_i32 m0, s45, 0xc000
	ds_read_b128 v[184:187], v144
	ds_read_b128 v[188:191], v144 offset:1024
	ds_read_b128 v[206:209], v144 offset:2048
	ds_read_b128 v[210:213], v144 offset:3072
	ds_read_b128 v[214:217], v144 offset:4096
	ds_read_b128 v[218:221], v144 offset:5120
	ds_read_b128 v[222:225], v144 offset:6144
	ds_read_b128 v[226:229], v144 offset:7168
	global_load_lds_dwordx4 v[230:231], off
	v_lshl_add_u64 v[230:231], s[22:23], 0, v[138:139]
	s_add_i32 m0, s45, 0xe000
	s_nop 0
	global_load_lds_dwordx4 v[230:231], off
	s_waitcnt vmcnt(8)
	s_waitcnt lgkmcnt(0)
	s_barrier
	s_setprio 1
	s_waitcnt lgkmcnt(0)
	v_mfma_f32_16x16x32_bf16 v[126:129], v[146:149], v[184:187], v[126:129]
	v_mfma_f32_16x16x32_bf16 v[126:129], v[150:153], v[188:191], v[126:129]
	v_mfma_f32_16x16x32_bf16 v[118:121], v[160:163], v[184:187], v[118:121]
	v_mfma_f32_16x16x32_bf16 v[118:121], v[164:167], v[188:191], v[118:121]
	v_mfma_f32_16x16x32_bf16 v[110:113], v[146:149], v[206:209], v[110:113]
	v_mfma_f32_16x16x32_bf16 v[110:113], v[150:153], v[210:213], v[110:113]
	v_mfma_f32_16x16x32_bf16 v[102:105], v[160:163], v[206:209], v[102:105]
	v_mfma_f32_16x16x32_bf16 v[102:105], v[164:167], v[210:213], v[102:105]
	v_mfma_f32_16x16x32_bf16 v[94:97], v[146:149], v[214:217], v[94:97]
	v_mfma_f32_16x16x32_bf16 v[94:97], v[150:153], v[218:221], v[94:97]
	v_mfma_f32_16x16x32_bf16 v[86:89], v[160:163], v[214:217], v[86:89]
	v_mfma_f32_16x16x32_bf16 v[86:89], v[164:167], v[218:221], v[86:89]
	v_mfma_f32_16x16x32_bf16 v[78:81], v[146:149], v[222:225], v[78:81]
	v_mfma_f32_16x16x32_bf16 v[78:81], v[150:153], v[226:229], v[78:81]
	v_mfma_f32_16x16x32_bf16 v[70:73], v[160:163], v[222:225], v[70:73]
	v_mfma_f32_16x16x32_bf16 v[70:73], v[164:167], v[226:229], v[70:73]
	s_setprio 0
	s_setprio 1
	v_mfma_f32_16x16x32_bf16 v[122:125], v[168:171], v[184:187], v[122:125]
	v_mfma_f32_16x16x32_bf16 v[122:125], v[172:175], v[188:191], v[122:125]
	v_mfma_f32_16x16x32_bf16 v[114:117], v[176:179], v[184:187], v[114:117]
	v_mfma_f32_16x16x32_bf16 v[114:117], v[180:183], v[188:191], v[114:117]
	v_mfma_f32_16x16x32_bf16 v[106:109], v[168:171], v[206:209], v[106:109]
	v_mfma_f32_16x16x32_bf16 v[106:109], v[172:175], v[210:213], v[106:109]
	v_mfma_f32_16x16x32_bf16 v[98:101], v[176:179], v[206:209], v[98:101]
	v_mfma_f32_16x16x32_bf16 v[98:101], v[180:183], v[210:213], v[98:101]
	v_mfma_f32_16x16x32_bf16 v[90:93], v[168:171], v[214:217], v[90:93]
	v_mfma_f32_16x16x32_bf16 v[90:93], v[172:175], v[218:221], v[90:93]
	v_mfma_f32_16x16x32_bf16 v[82:85], v[176:179], v[214:217], v[82:85]
	v_mfma_f32_16x16x32_bf16 v[82:85], v[180:183], v[218:221], v[82:85]
	v_mfma_f32_16x16x32_bf16 v[74:77], v[168:171], v[222:225], v[74:77]
	v_mfma_f32_16x16x32_bf16 v[74:77], v[172:175], v[226:229], v[74:77]
	v_mfma_f32_16x16x32_bf16 v[66:69], v[176:179], v[222:225], v[66:69]
	v_mfma_f32_16x16x32_bf16 v[66:69], v[180:183], v[226:229], v[66:69]
	s_setprio 0
	s_barrier
	s_add_i32 s22, s76, s29
	v_lshl_add_u64 v[230:231], s[40:41], 0, v[0:1]
	s_mov_b32 m0, s22
	ds_read_b128 v[184:187], v144 offset:16384
	ds_read_b128 v[188:191], v144 offset:17408
	ds_read_b128 v[206:209], v144 offset:18432
	ds_read_b128 v[210:213], v144 offset:19456
	ds_read_b128 v[214:217], v144 offset:20480
	ds_read_b128 v[218:221], v144 offset:21504
	ds_read_b128 v[222:225], v144 offset:22528
	ds_read_b128 v[226:229], v144 offset:23552
	global_load_lds_dwordx4 v[230:231], off
	s_add_i32 m0, s22, 0x2000
	s_add_u32 s22, s40, 0x40000
	v_lshl_add_u64 v[232:233], s[40:41], 0, v[130:131]
	s_addc_u32 s23, s41, 0
	s_add_i32 s58, s58, s29
	global_load_lds_dwordx4 v[232:233], off
	v_lshl_add_u64 v[234:235], s[22:23], 0, v[0:1]
	s_mov_b32 m0, s58
	s_nop 0
	global_load_lds_dwordx4 v[234:235], off
	v_lshl_add_u64 v[234:235], s[22:23], 0, v[130:131]
	s_add_i32 m0, s58, 0x2000
	s_nop 0
	global_load_lds_dwordx4 v[234:235], off
	v_lshl_add_u64 v[234:235], s[42:43], 0, v[134:135]
	s_mov_b32 m0, s45
	s_nop 0
	global_load_lds_dwordx4 v[234:235], off
	v_lshl_add_u64 v[234:235], s[42:43], 0, v[132:133]
	s_mov_b32 m0, s46
	s_nop 0
	global_load_lds_dwordx4 v[234:235], off
	s_waitcnt vmcnt(8)
	s_waitcnt lgkmcnt(0)
	s_barrier
; #define PG8_STAGE(bufoff, gbase, voff) do { _Pragma("unroll") for (int _i = 0; _i < 2; ++_i) \
;         __builtin_amdgcn_global_load_lds((const unsigned*)((const char*)(gbase) + (voff)[_i]), (PG8_LAS unsigned*)(lds + (bufoff) + ldsw + _i * 8192), 16, 0, 0); } while (0)
; #define PG8_LDA(dst, b, h) do { _Pragma("unroll") for (int m = 0; m < 4; ++m) _Pragma("unroll") for (int k = 0; k < 2; ++k) dst[m][k] = *(const PG8_LAS bf16x8*)(lds + PG8_SA(b, h) + aoff + m * 2048 + k * 1024); } while (0)
; #define PG8_LDB(dst, b, h) do { _Pragma("unroll") for (int n = 0; n < 2; ++n) _Pragma("unroll") for (int k = 0; k < 2; ++k) dst[n][k] = *(const PG8_LAS bf16x8*)(lds + PG8_SB(b, h) + boff + n * 2048 + k * 1024); } while (0)
; #define PG8_MMA(ai, bj, At, Bt) do { __builtin_amdgcn_s_setprio(1); _Pragma("unroll") for (int m = 0; m < 4; ++m) _Pragma("unroll") for (int n = 0; n < 2; ++n) _Pragma("unroll") for (int k = 0; k < 2; ++k) \
;         acc[ai][bj][m][n] = __builtin_amdgcn_mfma_f32_16x16x32_bf16(Bt[n][k], At[m][k], acc[ai][bj][m][n], 0, 0, 0); __builtin_amdgcn_s_setprio(0); } while (0)
; #define PG8_WAIT_V(n) asm volatile("s_waitcnt vmcnt(" #n ")" ::: "memory")
; #define PG8_WAIT_L(n) asm volatile("s_waitcnt lgkmcnt(" #n ")" ::: "memory")
; #define PG8_BAR __builtin_amdgcn_s_barrier()
; #define PG8_SCHED __builtin_amdgcn_sched_barrier(0)
; template <class Epi, class Sched, bool ALIGN_EPI = false, bool SP2 = false>
; __device__ __forceinline__ void gemm_phase(PG8_LAS unsigned char* lds, const Gemm g, const Sched& S, const Epi& E) {
;     ...
;             PG8_WAIT_V(8); PG8_WAIT_L(0); PG8_BAR; PG8_MMA(1, 0, At, B0); PG8_MMA(1, 1, At, B1); PG8_BAR; PG8_SCHED;
;             PG8_LDB(B0, 1, 0); PG8_LDB(B1, 1, 1); PG8_SCHED; PG8_LDA(At, 1, 0); PG8_STAGE(PG8_SA(0, 1), a2 + hstep, voffA);
;             PG8_WAIT_V(8); PG8_WAIT_L(0); PG8_BAR; PG8_MMA(0, 0, At, B0); PG8_MMA(0, 1, At, B1); PG8_BAR; PG8_SCHED;
	s_setprio 1
	s_waitcnt lgkmcnt(0)
	v_mfma_f32_16x16x32_bf16 v[62:65], v[146:149], v[184:187], v[62:65]
	v_mfma_f32_16x16x32_bf16 v[62:65], v[150:153], v[188:191], v[62:65]
	v_mfma_f32_16x16x32_bf16 v[54:57], v[160:163], v[184:187], v[54:57]
	v_mfma_f32_16x16x32_bf16 v[54:57], v[164:167], v[188:191], v[54:57]
	v_mfma_f32_16x16x32_bf16 v[46:49], v[146:149], v[206:209], v[46:49]
	v_mfma_f32_16x16x32_bf16 v[46:49], v[150:153], v[210:213], v[46:49]
	v_mfma_f32_16x16x32_bf16 v[38:41], v[160:163], v[206:209], v[38:41]
	v_mfma_f32_16x16x32_bf16 v[38:41], v[164:167], v[210:213], v[38:41]
	v_mfma_f32_16x16x32_bf16 v[30:33], v[146:149], v[214:217], v[30:33]
	v_mfma_f32_16x16x32_bf16 v[30:33], v[150:153], v[218:221], v[30:33]
	v_mfma_f32_16x16x32_bf16 v[22:25], v[160:163], v[214:217], v[22:25]
	v_mfma_f32_16x16x32_bf16 v[22:25], v[164:167], v[218:221], v[22:25]
	v_mfma_f32_16x16x32_bf16 v[14:17], v[146:149], v[222:225], v[14:17]
	v_mfma_f32_16x16x32_bf16 v[14:17], v[150:153], v[226:229], v[14:17]
	v_mfma_f32_16x16x32_bf16 v[6:9], v[160:163], v[222:225], v[6:9]
	v_mfma_f32_16x16x32_bf16 v[6:9], v[164:167], v[226:229], v[6:9]
	s_setprio 0
	s_setprio 1
	v_mfma_f32_16x16x32_bf16 v[58:61], v[168:171], v[184:187], v[58:61]
	v_mfma_f32_16x16x32_bf16 v[58:61], v[172:175], v[188:191], v[58:61]
	v_mfma_f32_16x16x32_bf16 v[50:53], v[176:179], v[184:187], v[50:53]
	v_mfma_f32_16x16x32_bf16 v[50:53], v[180:183], v[188:191], v[50:53]
	v_mfma_f32_16x16x32_bf16 v[42:45], v[168:171], v[206:209], v[42:45]
	v_mfma_f32_16x16x32_bf16 v[42:45], v[172:175], v[210:213], v[42:45]
	v_mfma_f32_16x16x32_bf16 v[34:37], v[176:179], v[206:209], v[34:37]
	v_mfma_f32_16x16x32_bf16 v[34:37], v[180:183], v[210:213], v[34:37]
	v_mfma_f32_16x16x32_bf16 v[26:29], v[168:171], v[214:217], v[26:29]
	v_mfma_f32_16x16x32_bf16 v[26:29], v[172:175], v[218:221], v[26:29]
	v_mfma_f32_16x16x32_bf16 v[18:21], v[176:179], v[214:217], v[18:21]
	v_mfma_f32_16x16x32_bf16 v[18:21], v[180:183], v[218:221], v[18:21]
	v_mfma_f32_16x16x32_bf16 v[10:13], v[168:171], v[222:225], v[10:13]
	v_mfma_f32_16x16x32_bf16 v[10:13], v[172:175], v[226:229], v[10:13]
	v_mfma_f32_16x16x32_bf16 v[2:5], v[176:179], v[222:225], v[2:5]
	v_mfma_f32_16x16x32_bf16 v[2:5], v[180:183], v[226:229], v[2:5]
	s_setprio 0
	s_barrier
	s_add_i32 s58, 0, 0x18000
	v_add_u32_e32 v145, s58, v142
	s_add_i32 s59, 0, 0x1c000
	ds_read_b128 v[146:149], v145
	ds_read_b128 v[150:153], v145 offset:1024
	ds_read_b128 v[160:163], v145 offset:2048
	ds_read_b128 v[164:167], v145 offset:3072
	v_add_u32_e32 v145, s59, v142
	ds_read_b128 v[168:171], v145
	ds_read_b128 v[172:175], v145 offset:1024
	ds_read_b128 v[176:179], v145 offset:2048
	ds_read_b128 v[180:183], v145 offset:3072
	s_add_u32 s22, s42, 0x40000
	s_addc_u32 s23, s43, 0
	s_mov_b32 m0, s47
	v_lshl_add_u64 v[234:235], s[22:23], 0, v[134:135]
	ds_read_b128 v[184:187], v144 offset:32768
	ds_read_b128 v[188:191], v144 offset:33792
	ds_read_b128 v[206:209], v144 offset:34816
	ds_read_b128 v[210:213], v144 offset:35840
	ds_read_b128 v[214:217], v144 offset:36864
	ds_read_b128 v[218:221], v144 offset:37888
	ds_read_b128 v[222:225], v144 offset:38912
	ds_read_b128 v[226:229], v144 offset:39936
	global_load_lds_dwordx4 v[234:235], off
	v_lshl_add_u64 v[234:235], s[22:23], 0, v[132:133]
	s_mov_b32 m0, s48
	s_nop 0
	global_load_lds_dwordx4 v[234:235], off
	s_waitcnt vmcnt(8)
	s_waitcnt lgkmcnt(0)
	s_barrier
	s_setprio 1
	s_waitcnt lgkmcnt(0)
	v_mfma_f32_16x16x32_bf16 v[126:129], v[146:149], v[184:187], v[126:129]
	v_mfma_f32_16x16x32_bf16 v[126:129], v[150:153], v[188:191], v[126:129]
	v_mfma_f32_16x16x32_bf16 v[118:121], v[160:163], v[184:187], v[118:121]
	v_mfma_f32_16x16x32_bf16 v[118:121], v[164:167], v[188:191], v[118:121]
	v_mfma_f32_16x16x32_bf16 v[110:113], v[146:149], v[206:209], v[110:113]
	v_mfma_f32_16x16x32_bf16 v[110:113], v[150:153], v[210:213], v[110:113]
	v_mfma_f32_16x16x32_bf16 v[102:105], v[160:163], v[206:209], v[102:105]
	v_mfma_f32_16x16x32_bf16 v[102:105], v[164:167], v[210:213], v[102:105]
	v_mfma_f32_16x16x32_bf16 v[94:97], v[146:149], v[214:217], v[94:97]
	v_mfma_f32_16x16x32_bf16 v[94:97], v[150:153], v[218:221], v[94:97]
	v_mfma_f32_16x16x32_bf16 v[86:89], v[160:163], v[214:217], v[86:89]
	v_mfma_f32_16x16x32_bf16 v[86:89], v[164:167], v[218:221], v[86:89]
	v_mfma_f32_16x16x32_bf16 v[78:81], v[146:149], v[222:225], v[78:81]
	v_mfma_f32_16x16x32_bf16 v[78:81], v[150:153], v[226:229], v[78:81]
	v_mfma_f32_16x16x32_bf16 v[70:73], v[160:163], v[222:225], v[70:73]
	v_mfma_f32_16x16x32_bf16 v[70:73], v[164:167], v[226:229], v[70:73]
	s_setprio 0
	s_setprio 1
	v_mfma_f32_16x16x32_bf16 v[122:125], v[168:171], v[184:187], v[122:125]
	v_mfma_f32_16x16x32_bf16 v[122:125], v[172:175], v[188:191], v[122:125]
	v_mfma_f32_16x16x32_bf16 v[114:117], v[176:179], v[184:187], v[114:117]
	v_mfma_f32_16x16x32_bf16 v[114:117], v[180:183], v[188:191], v[114:117]
	v_mfma_f32_16x16x32_bf16 v[106:109], v[168:171], v[206:209], v[106:109]
	v_mfma_f32_16x16x32_bf16 v[106:109], v[172:175], v[210:213], v[106:109]
	v_mfma_f32_16x16x32_bf16 v[98:101], v[176:179], v[206:209], v[98:101]
	v_mfma_f32_16x16x32_bf16 v[98:101], v[180:183], v[210:213], v[98:101]
	v_mfma_f32_16x16x32_bf16 v[90:93], v[168:171], v[214:217], v[90:93]
	v_mfma_f32_16x16x32_bf16 v[90:93], v[172:175], v[218:221], v[90:93]
	v_mfma_f32_16x16x32_bf16 v[82:85], v[176:179], v[214:217], v[82:85]
	v_mfma_f32_16x16x32_bf16 v[82:85], v[180:183], v[218:221], v[82:85]
	v_mfma_f32_16x16x32_bf16 v[74:77], v[168:171], v[222:225], v[74:77]
	v_mfma_f32_16x16x32_bf16 v[74:77], v[172:175], v[226:229], v[74:77]
	v_mfma_f32_16x16x32_bf16 v[66:69], v[176:179], v[222:225], v[66:69]
	v_mfma_f32_16x16x32_bf16 v[66:69], v[180:183], v[226:229], v[66:69]
	s_setprio 0
	s_barrier
; #define PG8_STAGE(bufoff, gbase, voff) do { _Pragma("unroll") for (int _i = 0; _i < 2; ++_i) \
;         __builtin_amdgcn_global_load_lds((const unsigned*)((const char*)(gbase) + (voff)[_i]), (PG8_LAS unsigned*)(lds + (bufoff) + ldsw + _i * 8192), 16, 0, 0); } while (0)
; #define PG8_LDA(dst, b, h) do { _Pragma("unroll") for (int m = 0; m < 4; ++m) _Pragma("unroll") for (int k = 0; k < 2; ++k) dst[m][k] = *(const PG8_LAS bf16x8*)(lds + PG8_SA(b, h) + aoff + m * 2048 + k * 1024); } while (0)
; #define PG8_MMA(ai, bj, At, Bt) do { __builtin_amdgcn_s_setprio(1); _Pragma("unroll") for (int m = 0; m < 4; ++m) _Pragma("unroll") for (int n = 0; n < 2; ++n) _Pragma("unroll") for (int k = 0; k < 2; ++k) \
;         acc[ai][bj][m][n] = __builtin_amdgcn_mfma_f32_16x16x32_bf16(Bt[n][k], At[m][k], acc[ai][bj][m][n], 0, 0, 0); __builtin_amdgcn_s_setprio(0); } while (0)
; #define PG8_WAIT_V(n) asm volatile("s_waitcnt vmcnt(" #n ")" ::: "memory")
; #define PG8_WAIT_L(n) asm volatile("s_waitcnt lgkmcnt(" #n ")" ::: "memory")
; #define PG8_BAR __builtin_amdgcn_s_barrier()
; #define PG8_SCHED __builtin_amdgcn_sched_barrier(0)
; template <class Epi, class Sched, bool ALIGN_EPI = false, bool SP2 = false>
; __device__ __forceinline__ void gemm_phase(PG8_LAS unsigned char* lds, const Gemm g, const Sched& S, const Epi& E) {
;     ...
;             PG8_LDA(At, 1, 1); PG8_STAGE(PG8_SB(1, 0), b3, voffB); PG8_STAGE(PG8_SB(1, 1), b3 + hstep, voffB); PG8_STAGE(PG8_SA(1, 0), a3, voffA);
;             PG8_WAIT_V(8); PG8_WAIT_L(0); PG8_BAR; PG8_MMA(1, 0, At, B0); PG8_MMA(1, 1, At, B1); PG8_BAR; PG8_SCHED;
	s_add_i32 s22, s58, s29
	v_lshl_add_u64 v[230:231], v[230:231], 0, s[38:39]
	s_mov_b32 m0, s22
	ds_read_b128 v[184:187], v144 offset:49152
	ds_read_b128 v[188:191], v144 offset:50176
	ds_read_b128 v[206:209], v144 offset:51200
	ds_read_b128 v[210:213], v144 offset:52224
	ds_read_b128 v[214:217], v144 offset:53248
	ds_read_b128 v[218:221], v144 offset:54272
	ds_read_b128 v[222:225], v144 offset:55296
	ds_read_b128 v[226:229], v144 offset:56320
	global_load_lds_dwordx4 v[230:231], off
	s_add_i32 m0, s22, 0x2000
	s_add_u32 s22, s40, 0x40080
	v_lshl_add_u64 v[230:231], v[232:233], 0, s[38:39]
	s_addc_u32 s23, s41, 0
	s_add_i32 s40, s59, s29
	global_load_lds_dwordx4 v[230:231], off
	v_lshl_add_u64 v[230:231], s[22:23], 0, v[0:1]
	s_mov_b32 m0, s40
	s_nop 0
	global_load_lds_dwordx4 v[230:231], off
	v_lshl_add_u64 v[230:231], s[22:23], 0, v[130:131]
	s_add_i32 m0, s40, 0x2000
	s_nop 0
	global_load_lds_dwordx4 v[230:231], off
	v_lshl_add_u64 v[230:231], s[26:27], 0, v[134:135]
	s_mov_b32 m0, s49
	s_nop 0
	global_load_lds_dwordx4 v[230:231], off
	v_lshl_add_u64 v[230:231], s[26:27], 0, v[132:133]
	s_mov_b32 m0, s50
	s_nop 0
	global_load_lds_dwordx4 v[230:231], off
	s_waitcnt vmcnt(8)
	s_waitcnt lgkmcnt(0)
	s_barrier
	s_setprio 1
	s_waitcnt lgkmcnt(0)
	v_mfma_f32_16x16x32_bf16 v[62:65], v[146:149], v[184:187], v[62:65]
	v_mfma_f32_16x16x32_bf16 v[62:65], v[150:153], v[188:191], v[62:65]
	v_mfma_f32_16x16x32_bf16 v[54:57], v[160:163], v[184:187], v[54:57]
	v_mfma_f32_16x16x32_bf16 v[54:57], v[164:167], v[188:191], v[54:57]
	v_mfma_f32_16x16x32_bf16 v[46:49], v[146:149], v[206:209], v[46:49]
	v_mfma_f32_16x16x32_bf16 v[46:49], v[150:153], v[210:213], v[46:49]
	v_mfma_f32_16x16x32_bf16 v[38:41], v[160:163], v[206:209], v[38:41]
	v_mfma_f32_16x16x32_bf16 v[38:41], v[164:167], v[210:213], v[38:41]
	v_mfma_f32_16x16x32_bf16 v[30:33], v[146:149], v[214:217], v[30:33]
	v_mfma_f32_16x16x32_bf16 v[30:33], v[150:153], v[218:221], v[30:33]
	v_mfma_f32_16x16x32_bf16 v[22:25], v[160:163], v[214:217], v[22:25]
	v_mfma_f32_16x16x32_bf16 v[22:25], v[164:167], v[218:221], v[22:25]
	v_mfma_f32_16x16x32_bf16 v[14:17], v[146:149], v[222:225], v[14:17]
	v_mfma_f32_16x16x32_bf16 v[14:17], v[150:153], v[226:229], v[14:17]
	v_mfma_f32_16x16x32_bf16 v[6:9], v[160:163], v[222:225], v[6:9]
	v_mfma_f32_16x16x32_bf16 v[6:9], v[164:167], v[226:229], v[6:9]
	s_setprio 0
	s_setprio 1
	v_mfma_f32_16x16x32_bf16 v[58:61], v[168:171], v[184:187], v[58:61]
	v_mfma_f32_16x16x32_bf16 v[58:61], v[172:175], v[188:191], v[58:61]
	v_mfma_f32_16x16x32_bf16 v[50:53], v[176:179], v[184:187], v[50:53]
	v_mfma_f32_16x16x32_bf16 v[50:53], v[180:183], v[188:191], v[50:53]
	v_mfma_f32_16x16x32_bf16 v[42:45], v[168:171], v[206:209], v[42:45]
	v_mfma_f32_16x16x32_bf16 v[42:45], v[172:175], v[210:213], v[42:45]
	v_mfma_f32_16x16x32_bf16 v[34:37], v[176:179], v[206:209], v[34:37]
	v_mfma_f32_16x16x32_bf16 v[34:37], v[180:183], v[210:213], v[34:37]
	v_mfma_f32_16x16x32_bf16 v[26:29], v[168:171], v[214:217], v[26:29]
	v_mfma_f32_16x16x32_bf16 v[26:29], v[172:175], v[218:221], v[26:29]
	v_mfma_f32_16x16x32_bf16 v[18:21], v[176:179], v[214:217], v[18:21]
	v_mfma_f32_16x16x32_bf16 v[18:21], v[180:183], v[218:221], v[18:21]
	v_mfma_f32_16x16x32_bf16 v[10:13], v[168:171], v[222:225], v[10:13]
	v_mfma_f32_16x16x32_bf16 v[10:13], v[172:175], v[226:229], v[10:13]
	v_mfma_f32_16x16x32_bf16 v[2:5], v[176:179], v[222:225], v[2:5]
	v_mfma_f32_16x16x32_bf16 v[2:5], v[180:183], v[226:229], v[2:5]
	s_setprio 0
	s_barrier
	s_add_i32 s57, s57, 2
	s_add_u32 s55, s55, 0x100
	s_addc_u32 s56, s56, 0
	s_cmp_gt_u32 s57, 13
	s_mov_b64 s[22:23], s[24:25]
	s_cbranch_scc0 .LBB0_409
	s_and_b64 vcc, exec, s[6:7]
	s_cbranch_vccz .LBB0_412
	s_barrier
